# adds natten: entering K|V row + key stats requested behind the query waits and waited at their use (end of row step), to v019
# speedup vs baseline: 1.0073x; 1.0073x over previous
.LBB0_814:
	v_med3_u32 v24, s12, 4, 28
	v_med3_u32 v25, s12, 3, 27
	s_cmp_lg_u32 s13, 1
	v_add_u32_e32 v26, -1, v24
	s_cselect_b64 s[58:59], -1, 0
	v_cmp_ne_u32_e32 vcc, v25, v26
	s_and_b64 s[34:35], s[58:59], vcc
	v_cndmask_b32_e64 v25, 0, 1, s[34:35]
	v_cmp_ne_u32_e64 s[10:11], 1, v25
	v_readfirstlane_b32 s83, v24
	s_waitcnt vmcnt(1)
	v_lshlrev_b32_e32 v46, 16, v0
	v_and_b32_e32 v47, 0xffff0000, v0
	v_lshlrev_b32_e32 v42, 16, v1
	v_and_b32_e32 v43, 0xffff0000, v1
	v_pk_mul_f32 v[62:63], v[46:47], v[46:47]
	v_pk_mul_f32 v[58:59], v[42:43], v[42:43]
	v_add_f32_e32 v62, v62, v63
	v_lshlrev_b32_e32 v38, 16, v2
	v_and_b32_e32 v39, 0xffff0000, v2
	v_add_f32_e32 v58, v58, v62
	v_pk_mul_f32 v[54:55], v[38:39], v[38:39]
	v_add_f32_e32 v58, v59, v58
	v_lshlrev_b32_e32 v34, 16, v3
	v_and_b32_e32 v35, 0xffff0000, v3
	v_add_f32_e32 v54, v54, v58
	v_pk_mul_f32 v[50:51], v[34:35], v[34:35]
	v_add_f32_e32 v54, v55, v54
	s_waitcnt vmcnt(0)
	s_and_b64 vcc, exec, s[10:11]
	s_cbranch_vccnz .Lmy_noslide
	s_add_i32 s86, s83, 4
	s_mul_i32 s88, s86, 0x30000
	s_mov_b32 s89, 0
	v_lshl_add_u64 v[24:25], s[88:89], 1, v[84:85]
	v_lshl_add_u64 v[26:27], v[24:25], 0, s[54:55]
	global_load_dwordx4 v[28:31], v[24:25], off offset:2048
	s_nop 0
	global_load_dwordx4 v[24:27], v[26:27], off offset:2048
	v_mov_b32_e32 v79, 0x358637bd
	s_and_saveexec_b64 s[98:99], s[6:7]
	s_cbranch_execz .Lmy_s817
	s_lshl_b32 s88, s86, 6
	v_lshl_add_u64 v[222:223], s[88:89], 2, v[86:87]
	v_add_co_u32_e32 v224, vcc, 0x20000, v222
	s_nop 1
	v_addc_co_u32_e32 v225, vcc, 0, v223, vcc
	global_load_dword v226, v[222:223], off
	s_nop 0
	global_load_dword v227, v[224:225], off
.Lmy_s817:
	s_or_b64 exec, exec, s[98:99]
	s_branch .Lmy_slide_done

.Lmy_slide_done:
	v_lshlrev_b32_e32 v44, 16, v4
	v_and_b32_e32 v45, 0xffff0000, v4
	v_add_f32_e32 v50, v50, v54
	v_pk_mul_f32 v[60:61], v[44:45], v[44:45]
	v_add_f32_e32 v50, v51, v50
	v_lshlrev_b32_e32 v40, 16, v5
	v_and_b32_e32 v41, 0xffff0000, v5
	v_add_f32_e32 v50, v60, v50
	v_pk_mul_f32 v[56:57], v[40:41], v[40:41]
	v_add_f32_e32 v50, v61, v50
	v_lshlrev_b32_e32 v36, 16, v6
	v_and_b32_e32 v37, 0xffff0000, v6
	v_add_f32_e32 v50, v56, v50
	v_pk_mul_f32 v[52:53], v[36:37], v[36:37]
	v_add_f32_e32 v50, v57, v50
	v_lshlrev_b32_e32 v32, 16, v7
	v_and_b32_e32 v33, 0xffff0000, v7
	v_add_f32_e32 v50, v52, v50
	v_pk_mul_f32 v[48:49], v[32:33], v[32:33]
	v_add_f32_e32 v50, v53, v50
	v_add_f32_e32 v48, v48, v50
	v_add_f32_e32 v48, v49, v48
	ds_bpermute_b32 v49, v97, v48
	s_andn2_b64 vcc, exec, s[58:59]
	s_waitcnt lgkmcnt(0)
	v_add_f32_e32 v48, v48, v49
	ds_bpermute_b32 v49, v98, v48
	s_cbranch_vccnz .LBB0_821
	global_load_dwordx4 v[0:3], v[92:93], off
	global_load_dwordx4 v[4:7], v[92:93], off offset:64

.LBB0_891:
	s_and_b64 vcc, exec, s[10:11]
	s_cbranch_vccnz .LBB0_813
	s_cmp_lt_u32 s91, 4
	s_cbranch_scc1 .Lmy_kh0
	s_waitcnt vmcnt(2)
	s_branch .Lmy_wdone
.Lmy_kh0:
	s_waitcnt vmcnt(6)
.Lmy_wdone:
	s_and_b32 s10, s83, 7
	s_xor_b32 s10, s10, 4
	s_mulk_i32 s10, 0x4100
	s_add_i32 s22, s10, 0
	v_add_u32_e32 v32, s22, v67
	ds_write_b128 v32, v[28:31]
	ds_write_b128 v32, v[24:27] offset:8192
	s_and_saveexec_b64 s[10:11], s[6:7]
	s_cbranch_execz .LBB0_812
	v_add_f32_e32 v226, v226, v227
	v_fmamk_f32 v79, v226, 0x3c800000, v73
	v_rsq_f32_e32 v24, v79
	v_add_u32_e32 v25, s22, v66
	ds_write_b32 v25, v24 offset:16384
	s_branch .LBB0_812
